# main GEMM K-loop: per-phase s_setprio 1/0 flips removed (all waves stay at priority 0)
# speedup vs baseline: 1.0227x; 1.0096x over previous
; #define LDA(dst, b, h) for (int m = 0; m < 4; ++m) for (int k = 0; k < 2; ++k) \
;     dst[m][k] = *reinterpret_cast<const bf16x8*>(SA(b, h) + lds_byte(wr * 64 + m * 16 + fr, k * 32 + fq * 8))
; #define LDB(dst, b, h) for (int n = 0; n < 2; ++n) for (int k = 0; k < 2; ++k) \
;     dst[n][k] = *reinterpret_cast<const bf16x8*>(SB(b, h) + lds_byte(wc * 32 + n * 16 + fr, k * 32 + fq * 8))
; #define MMA(ai, bj, At_, Bt_) do { __builtin_amdgcn_s_setprio(1); \
;     for (int m = 0; m < 4; ++m) for (int n = 0; n < 2; ++n) for (int k = 0; k < 2; ++k) \
;       acc[ai][bj][m][n] = __builtin_amdgcn_mfma_f32_16x16x32_bf16(Bt_[n][k], At_[m][k], acc[ai][bj][m][n], 0, 0, 0); \
;     __builtin_amdgcn_s_setprio(0); } while (0)
; #define WAIT_L(n) asm volatile("s_waitcnt lgkmcnt(" #n ")" ::: "memory")
; #define BAR __builtin_amdgcn_s_barrier()
; #define SCHED __builtin_amdgcn_sched_barrier(0)
; #define STG(P, PTR, LD, O0) do { const bf16_t* _g = (PTR); \
;     __builtin_amdgcn_global_load_lds((const unsigned*)(_g + O0), (lds_u32*)((P) + swave * 1024), 16, 0, 0); \
;     __builtin_amdgcn_global_load_lds((const unsigned*)(_g + (size_t)64 * (LD) + O0), (lds_u32*)((P) + swave * 1024 + 8192), 16, 0, 0); } while (0)
; #define LDA(dst, b, h) for (int m = 0; m < 4; ++m) for (int k = 0; k < 2; ++k) \
;     dst[m][k] = *reinterpret_cast<const bf16x8*>(SA(b, h) + lds_byte(wr * 64 + m * 16 + fr, k * 32 + fq * 8))
; #define LDB(dst, b, h) for (int n = 0; n < 2; ++n) for (int k = 0; k < 2; ++k) \
;     dst[n][k] = *reinterpret_cast<const bf16x8*>(SB(b, h) + lds_byte(wc * 32 + n * 16 + fr, k * 32 + fq * 8))
; #define WAIT_L(n) asm volatile("s_waitcnt lgkmcnt(" #n ")" ::: "memory")
; #define BAR __builtin_amdgcn_s_barrier()
; #define SCHED __builtin_amdgcn_sched_barrier(0)
; __device__ __forceinline__ void gemm_stream(int swave, const GemmJob& J, char* shm, int vb, int G) {
;     ...
;       LDB(B0, 0, 0); SCHED; LDA(At, 0, 0); STGA(SA(1, 1), cA, cA1, t + 1, 1);
;       WAIT_L(8); BAR; WAIT_L(0); MMA(0, 0, At, B0); BAR; SCHED;
;       LDB(B1, 0, 1); STG(SB(0, 0), b2, ldb, offB0);
;       BAR; WAIT_L(0); MMA(0, 1, At, B1); BAR;
;       LDA(At, 0, 1); STGA(SA(0, 0), xA, xA1, k2, 0);
;       BAR; WAIT_L(0); MMA(1, 0, At, B0); BAR; SCHED;
;       STG(SB(0, 1), b2 + hB, ldb, offB0);
.LBB0_729:
	ds_read_b128 v[164:167], v139
	ds_read_b128 v[168:171], v139 offset:1024
	ds_read_b128 v[172:175], v139 offset:2048
	ds_read_b128 v[176:179], v139 offset:3072
	s_cmp_eq_u32 s49, s29
	s_cselect_b64 s[68:69], -1, 0
	s_and_b64 s[64:65], s[68:69], exec
	s_cselect_b32 s52, s10, s8
	s_cselect_b32 s64, s11, s9
	s_add_i32 s33, s2, 2
	s_and_b64 s[68:69], s[68:69], exec
	s_cselect_b32 s71, s15, s21
	s_cselect_b32 s70, s14, s20
	s_cselect_b32 s68, 0, s33
	s_cselect_b32 s65, s12, s16
	s_cselect_b32 s66, s13, s17
	s_or_b32 s2, s2, 1
	s_cmp_lt_u32 s2, s36
	s_cselect_b64 vcc, -1, 0
	s_and_b64 s[2:3], vcc, exec
	s_cselect_b32 s3, 0, s36
	s_cselect_b32 s2, s38, s37
	s_not_b32 s3, s3
	s_add_i32 s94, s3, s29
	s_and_b64 s[72:73], vcc, exec
	s_cselect_b32 s3, s9, s17
	s_cselect_b32 s69, s8, s16
	s_lshl_b64 s[72:73], s[94:95], 7
	s_add_u32 s69, s69, s72
	s_addc_u32 s74, s3, s73
	s_mov_b32 s3, s95
	s_lshl_b64 s[72:73], s[2:3], 8
	s_add_u32 s72, s69, s72
	v_cndmask_b32_e32 v2, v138, v0, vcc
	s_addc_u32 s73, s74, s73
	s_add_i32 m0, s42, 0xc000
	s_lshl_b64 s[2:3], s[2:3], 7
	v_lshlrev_b64 v[212:213], 1, v[2:3]
	s_add_u32 s2, s72, s2
	v_lshl_add_u64 v[214:215], s[72:73], 0, v[212:213]
	s_addc_u32 s3, s73, s3
	ds_read_b128 v[180:183], v144
	ds_read_b128 v[184:187], v144 offset:1024
	ds_read_b128 v[188:191], v145
	ds_read_b128 v[192:195], v145 offset:1024
	ds_read_b128 v[196:199], v159
	ds_read_b128 v[200:203], v159 offset:1024
	ds_read_b128 v[204:207], v160
	ds_read_b128 v[208:211], v160 offset:1024
	global_load_lds_dwordx4 v[214:215], off
	v_lshl_add_u64 v[212:213], s[2:3], 0, v[212:213]
	s_add_i32 m0, s42, 0xe000
	s_nop 0
	global_load_lds_dwordx4 v[212:213], off
	s_waitcnt lgkmcnt(8)
	s_barrier
	s_waitcnt lgkmcnt(0)
	s_waitcnt lgkmcnt(0)
	v_mfma_f32_16x16x32_bf16 v[128:131], v[164:167], v[180:183], v[128:131]
	v_mfma_f32_16x16x32_bf16 v[124:127], v[172:175], v[180:183], v[124:127]
	v_mfma_f32_16x16x32_bf16 v[120:123], v[164:167], v[188:191], v[120:123]
	v_mfma_f32_16x16x32_bf16 v[116:119], v[172:175], v[188:191], v[116:119]
	v_mfma_f32_16x16x32_bf16 v[104:107], v[164:167], v[196:199], v[104:107]
	v_mfma_f32_16x16x32_bf16 v[100:103], v[172:175], v[196:199], v[100:103]
	v_mfma_f32_16x16x32_bf16 v[88:91], v[164:167], v[204:207], v[88:91]
	v_mfma_f32_16x16x32_bf16 v[84:87], v[172:175], v[204:207], v[84:87]
	v_mfma_f32_16x16x32_bf16 v[128:131], v[168:171], v[184:187], v[128:131]
	v_mfma_f32_16x16x32_bf16 v[124:127], v[176:179], v[184:187], v[124:127]
	v_mfma_f32_16x16x32_bf16 v[120:123], v[168:171], v[192:195], v[120:123]
	v_mfma_f32_16x16x32_bf16 v[116:119], v[176:179], v[192:195], v[116:119]
	v_mfma_f32_16x16x32_bf16 v[104:107], v[168:171], v[200:203], v[104:107]
	v_mfma_f32_16x16x32_bf16 v[100:103], v[176:179], v[200:203], v[100:103]
	v_mfma_f32_16x16x32_bf16 v[88:91], v[168:171], v[208:211], v[88:91]
	v_mfma_f32_16x16x32_bf16 v[84:87], v[176:179], v[208:211], v[84:87]
	s_barrier
	s_add_u32 s2, s70, s0
	s_mov_b32 m0, s43
	v_lshl_add_u64 v[228:229], s[70:71], 0, v[136:137]
	s_addc_u32 s3, s71, s1
	ds_read_b128 v[212:215], v161
	ds_read_b128 v[216:219], v161 offset:1024
	ds_read_b128 v[220:223], v161 offset:2048
	ds_read_b128 v[224:227], v161 offset:3072
	global_load_lds_dwordx4 v[228:229], off
	v_lshl_add_u64 v[230:231], s[2:3], 0, v[136:137]
	s_mov_b32 m0, s44
	s_nop 0
	global_load_lds_dwordx4 v[230:231], off
	s_barrier
	s_waitcnt lgkmcnt(0)
	s_waitcnt lgkmcnt(0)
	v_mfma_f32_16x16x32_bf16 v[112:115], v[212:215], v[180:183], v[112:115]
	v_mfma_f32_16x16x32_bf16 v[108:111], v[220:223], v[180:183], v[108:111]
	v_mfma_f32_16x16x32_bf16 v[96:99], v[212:215], v[188:191], v[96:99]
	v_mfma_f32_16x16x32_bf16 v[92:95], v[220:223], v[188:191], v[92:95]
	v_mfma_f32_16x16x32_bf16 v[80:83], v[212:215], v[196:199], v[80:83]
	v_mfma_f32_16x16x32_bf16 v[76:79], v[220:223], v[196:199], v[76:79]
	v_mfma_f32_16x16x32_bf16 v[72:75], v[212:215], v[204:207], v[72:75]
	v_mfma_f32_16x16x32_bf16 v[68:71], v[220:223], v[204:207], v[68:71]
	v_mfma_f32_16x16x32_bf16 v[112:115], v[216:219], v[184:187], v[112:115]
	v_mfma_f32_16x16x32_bf16 v[108:111], v[224:227], v[184:187], v[108:111]
	v_mfma_f32_16x16x32_bf16 v[96:99], v[216:219], v[192:195], v[96:99]
	v_mfma_f32_16x16x32_bf16 v[92:95], v[224:227], v[192:195], v[92:95]
	v_mfma_f32_16x16x32_bf16 v[80:83], v[216:219], v[200:203], v[80:83]
	v_mfma_f32_16x16x32_bf16 v[76:79], v[224:227], v[200:203], v[76:79]
	v_mfma_f32_16x16x32_bf16 v[72:75], v[216:219], v[208:211], v[72:75]
	v_mfma_f32_16x16x32_bf16 v[68:71], v[224:227], v[208:211], v[68:71]
	s_cmp_lt_u32 s68, s36
	s_cselect_b64 vcc, -1, 0
	s_and_b64 s[70:71], vcc, exec
	s_cselect_b32 s70, s38, s37
	s_sub_i32 s69, s68, s36
	s_min_u32 s94, s68, s69
	s_and_b64 s[72:73], vcc, exec
	s_cselect_b32 s69, s64, s66
	s_cselect_b32 s71, s52, s65
	s_lshl_b64 s[72:73], s[94:95], 7
	v_cndmask_b32_e32 v2, v138, v0, vcc
	s_add_u32 s72, s71, s72
	s_mov_b32 s71, s95
	s_addc_u32 s73, s69, s73
	v_lshlrev_b64 v[232:233], 1, v[2:3]
	s_lshl_b64 s[70:71], s[70:71], 7
	v_lshl_add_u64 v[234:235], s[72:73], 0, v[232:233]
	s_add_u32 s72, s72, s70
	s_mov_b32 m0, s42
	s_addc_u32 s73, s73, s71
	s_barrier
	ds_read_b128 v[180:183], v144 offset:16384
	ds_read_b128 v[184:187], v144 offset:17408
	ds_read_b128 v[188:191], v145 offset:16384
	ds_read_b128 v[192:195], v145 offset:17408
	ds_read_b128 v[196:199], v159 offset:16384
	ds_read_b128 v[200:203], v159 offset:17408
	ds_read_b128 v[204:207], v160 offset:16384
	ds_read_b128 v[208:211], v160 offset:17408
	global_load_lds_dwordx4 v[234:235], off
	v_lshl_add_u64 v[234:235], s[72:73], 0, v[232:233]
	s_mov_b32 m0, s39
	s_nop 0
	global_load_lds_dwordx4 v[234:235], off
	s_barrier
; #define LDA(dst, b, h) for (int m = 0; m < 4; ++m) for (int k = 0; k < 2; ++k) \
;     dst[m][k] = *reinterpret_cast<const bf16x8*>(SA(b, h) + lds_byte(wr * 64 + m * 16 + fr, k * 32 + fq * 8))
; #define LDB(dst, b, h) for (int n = 0; n < 2; ++n) for (int k = 0; k < 2; ++k) \
;     dst[n][k] = *reinterpret_cast<const bf16x8*>(SB(b, h) + lds_byte(wc * 32 + n * 16 + fr, k * 32 + fq * 8))
; #define MMA(ai, bj, At_, Bt_) do { __builtin_amdgcn_s_setprio(1); \
;     for (int m = 0; m < 4; ++m) for (int n = 0; n < 2; ++n) for (int k = 0; k < 2; ++k) \
;       acc[ai][bj][m][n] = __builtin_amdgcn_mfma_f32_16x16x32_bf16(Bt_[n][k], At_[m][k], acc[ai][bj][m][n], 0, 0, 0); \
;     __builtin_amdgcn_s_setprio(0); } while (0)
; #define WAIT_V(n) asm volatile("s_waitcnt vmcnt(" #n ")" ::: "memory")
; #define WAIT_L(n) asm volatile("s_waitcnt lgkmcnt(" #n ")" ::: "memory")
; #define BAR __builtin_amdgcn_s_barrier()
; #define SCHED __builtin_amdgcn_sched_barrier(0)
; #define STG(P, PTR, LD, O0) do { const bf16_t* _g = (PTR); \
;     __builtin_amdgcn_global_load_lds((const unsigned*)(_g + O0), (lds_u32*)((P) + swave * 1024), 16, 0, 0); \
;     __builtin_amdgcn_global_load_lds((const unsigned*)(_g + (size_t)64 * (LD) + O0), (lds_u32*)((P) + swave * 1024 + 8192), 16, 0, 0); } while (0)
; #define LDA(dst, b, h) for (int m = 0; m < 4; ++m) for (int k = 0; k < 2; ++k) \
;     dst[m][k] = *reinterpret_cast<const bf16x8*>(SA(b, h) + lds_byte(wr * 64 + m * 16 + fr, k * 32 + fq * 8))
; #define LDB(dst, b, h) for (int n = 0; n < 2; ++n) for (int k = 0; k < 2; ++k) \
;     dst[n][k] = *reinterpret_cast<const bf16x8*>(SB(b, h) + lds_byte(wc * 32 + n * 16 + fr, k * 32 + fq * 8))
; #define WAIT_V(n) asm volatile("s_waitcnt vmcnt(" #n ")" ::: "memory")
; #define WAIT_L(n) asm volatile("s_waitcnt lgkmcnt(" #n ")" ::: "memory")
; __device__ __forceinline__ void gemm_stream(int swave, const GemmJob& J, char* shm, int vb, int G) {
;     ...
;       BAR; WAIT_L(0); MMA(1, 0, At, B0); BAR; SCHED;
;       STG(SB(0, 1), b2 + hB, ldb, offB0);
;       WAIT_V(6); BAR; MMA(1, 1, At, B1); BAR;
;       LDB(B0, 1, 0); SCHED; LDA(At, 1, 0); STGA(SA(0, 1), xA, xA1, k2, 1);
;       WAIT_L(8); BAR; WAIT_L(0); MMA(0, 0, At, B0); BAR; SCHED;
;       LDB(B1, 1, 1); STG(SB(1, 0), b3, ldb, offB0);
;       BAR; WAIT_L(0); MMA(0, 1, At, B1); BAR;
;       LDA(At, 1, 1); STGA(SA(1, 0), xA, xA1, k2 + 1, 0);
	s_waitcnt lgkmcnt(0)
	s_waitcnt lgkmcnt(0)
	v_mfma_f32_16x16x32_bf16 v[64:67], v[164:167], v[180:183], v[64:67]
	v_mfma_f32_16x16x32_bf16 v[60:63], v[172:175], v[180:183], v[60:63]
	v_mfma_f32_16x16x32_bf16 v[56:59], v[164:167], v[188:191], v[56:59]
	v_mfma_f32_16x16x32_bf16 v[52:55], v[172:175], v[188:191], v[52:55]
	v_mfma_f32_16x16x32_bf16 v[40:43], v[164:167], v[196:199], v[40:43]
	v_mfma_f32_16x16x32_bf16 v[36:39], v[172:175], v[196:199], v[36:39]
	v_mfma_f32_16x16x32_bf16 v[24:27], v[164:167], v[204:207], v[24:27]
	v_mfma_f32_16x16x32_bf16 v[20:23], v[172:175], v[204:207], v[20:23]
	v_mfma_f32_16x16x32_bf16 v[64:67], v[168:171], v[184:187], v[64:67]
	v_mfma_f32_16x16x32_bf16 v[60:63], v[176:179], v[184:187], v[60:63]
	v_mfma_f32_16x16x32_bf16 v[56:59], v[168:171], v[192:195], v[56:59]
	v_mfma_f32_16x16x32_bf16 v[52:55], v[176:179], v[192:195], v[52:55]
	v_mfma_f32_16x16x32_bf16 v[40:43], v[168:171], v[200:203], v[40:43]
	v_mfma_f32_16x16x32_bf16 v[36:39], v[176:179], v[200:203], v[36:39]
	v_mfma_f32_16x16x32_bf16 v[24:27], v[168:171], v[208:211], v[24:27]
	v_mfma_f32_16x16x32_bf16 v[20:23], v[176:179], v[208:211], v[20:23]
	s_barrier
	s_add_u32 s2, s2, s0
	s_addc_u32 s3, s3, s1
	v_lshl_add_u64 v[234:235], s[2:3], 0, v[136:137]
	s_add_u32 s2, s2, s0
	s_mov_b32 m0, s45
	s_addc_u32 s3, s3, s1
	global_load_lds_dwordx4 v[234:235], off
	v_lshl_add_u64 v[236:237], s[2:3], 0, v[136:137]
	s_mov_b32 m0, s46
	s_nop 0
	global_load_lds_dwordx4 v[236:237], off
	s_waitcnt vmcnt(6)
	s_barrier
	v_mfma_f32_16x16x32_bf16 v[48:51], v[212:215], v[180:183], v[48:51]
	v_mfma_f32_16x16x32_bf16 v[44:47], v[220:223], v[180:183], v[44:47]
	v_mfma_f32_16x16x32_bf16 v[32:35], v[212:215], v[188:191], v[32:35]
	v_mfma_f32_16x16x32_bf16 v[28:31], v[220:223], v[188:191], v[28:31]
	v_mfma_f32_16x16x32_bf16 v[16:19], v[212:215], v[196:199], v[16:19]
	v_mfma_f32_16x16x32_bf16 v[12:15], v[220:223], v[196:199], v[12:15]
	v_mfma_f32_16x16x32_bf16 v[8:11], v[212:215], v[204:207], v[8:11]
	v_mfma_f32_16x16x32_bf16 v[4:7], v[220:223], v[204:207], v[4:7]
	v_mfma_f32_16x16x32_bf16 v[48:51], v[216:219], v[184:187], v[48:51]
	v_mfma_f32_16x16x32_bf16 v[44:47], v[224:227], v[184:187], v[44:47]
	v_mfma_f32_16x16x32_bf16 v[32:35], v[216:219], v[192:195], v[32:35]
	v_mfma_f32_16x16x32_bf16 v[28:31], v[224:227], v[192:195], v[28:31]
	v_mfma_f32_16x16x32_bf16 v[16:19], v[216:219], v[200:203], v[16:19]
	v_mfma_f32_16x16x32_bf16 v[12:15], v[224:227], v[200:203], v[12:15]
	v_mfma_f32_16x16x32_bf16 v[8:11], v[216:219], v[208:211], v[8:11]
	v_mfma_f32_16x16x32_bf16 v[4:7], v[224:227], v[208:211], v[4:7]
	s_barrier
	ds_read_b128 v[164:167], v162
	ds_read_b128 v[168:171], v162 offset:1024
	ds_read_b128 v[172:175], v162 offset:2048
	ds_read_b128 v[176:179], v162 offset:3072
	s_add_u32 s2, s72, s70
	s_addc_u32 s3, s73, s71
	v_lshl_add_u64 v[212:213], s[2:3], 0, v[232:233]
	s_add_u32 s2, s2, s70
	s_mov_b32 m0, s47
	s_addc_u32 s3, s3, s71
	ds_read_b128 v[180:183], v144 offset:32768
	ds_read_b128 v[184:187], v144 offset:33792
	ds_read_b128 v[188:191], v145 offset:32768
	ds_read_b128 v[192:195], v145 offset:33792
	ds_read_b128 v[196:199], v159 offset:32768
	ds_read_b128 v[200:203], v159 offset:33792
	ds_read_b128 v[204:207], v160 offset:32768
	ds_read_b128 v[208:211], v160 offset:33792
	global_load_lds_dwordx4 v[212:213], off
	v_lshl_add_u64 v[212:213], s[2:3], 0, v[232:233]
	s_mov_b32 m0, s48
	s_nop 0
	global_load_lds_dwordx4 v[212:213], off
	s_waitcnt lgkmcnt(8)
	s_barrier
	s_waitcnt lgkmcnt(0)
	s_waitcnt lgkmcnt(0)
	v_mfma_f32_16x16x32_bf16 v[128:131], v[164:167], v[180:183], v[128:131]
	v_mfma_f32_16x16x32_bf16 v[124:127], v[172:175], v[180:183], v[124:127]
	v_mfma_f32_16x16x32_bf16 v[120:123], v[164:167], v[188:191], v[120:123]
	v_mfma_f32_16x16x32_bf16 v[116:119], v[172:175], v[188:191], v[116:119]
	v_mfma_f32_16x16x32_bf16 v[104:107], v[164:167], v[196:199], v[104:107]
	v_mfma_f32_16x16x32_bf16 v[100:103], v[172:175], v[196:199], v[100:103]
	v_mfma_f32_16x16x32_bf16 v[88:91], v[164:167], v[204:207], v[88:91]
	v_mfma_f32_16x16x32_bf16 v[84:87], v[172:175], v[204:207], v[84:87]
	v_mfma_f32_16x16x32_bf16 v[128:131], v[168:171], v[184:187], v[128:131]
	v_mfma_f32_16x16x32_bf16 v[124:127], v[176:179], v[184:187], v[124:127]
	v_mfma_f32_16x16x32_bf16 v[120:123], v[168:171], v[192:195], v[120:123]
	v_mfma_f32_16x16x32_bf16 v[116:119], v[176:179], v[192:195], v[116:119]
	v_mfma_f32_16x16x32_bf16 v[104:107], v[168:171], v[200:203], v[104:107]
	v_mfma_f32_16x16x32_bf16 v[100:103], v[176:179], v[200:203], v[100:103]
	v_mfma_f32_16x16x32_bf16 v[88:91], v[168:171], v[208:211], v[88:91]
	v_mfma_f32_16x16x32_bf16 v[84:87], v[176:179], v[208:211], v[84:87]
	s_barrier
	v_lshl_add_u64 v[228:229], v[228:229], 0, s[22:23]
	s_add_i32 m0, s42, 0x18000
	ds_read_b128 v[212:215], v163
	ds_read_b128 v[216:219], v163 offset:1024
	ds_read_b128 v[220:223], v163 offset:2048
	ds_read_b128 v[224:227], v163 offset:3072
	global_load_lds_dwordx4 v[228:229], off
	v_lshl_add_u64 v[228:229], v[230:231], 0, s[22:23]
	s_add_i32 m0, s42, 0x1a000
	s_nop 0
	global_load_lds_dwordx4 v[228:229], off
	s_barrier
; #define LDA(dst, b, h) for (int m = 0; m < 4; ++m) for (int k = 0; k < 2; ++k) \
;     dst[m][k] = *reinterpret_cast<const bf16x8*>(SA(b, h) + lds_byte(wr * 64 + m * 16 + fr, k * 32 + fq * 8))
; #define MMA(ai, bj, At_, Bt_) do { __builtin_amdgcn_s_setprio(1); \
;     for (int m = 0; m < 4; ++m) for (int n = 0; n < 2; ++n) for (int k = 0; k < 2; ++k) \
;       acc[ai][bj][m][n] = __builtin_amdgcn_mfma_f32_16x16x32_bf16(Bt_[n][k], At_[m][k], acc[ai][bj][m][n], 0, 0, 0); \
;     __builtin_amdgcn_s_setprio(0); } while (0)
; #define WAIT_V(n) asm volatile("s_waitcnt vmcnt(" #n ")" ::: "memory")
; #define WAIT_L(n) asm volatile("s_waitcnt lgkmcnt(" #n ")" ::: "memory")
; #define BAR __builtin_amdgcn_s_barrier()
; #define SCHED __builtin_amdgcn_sched_barrier(0)
; #define STG(P, PTR, LD, O0) do { const bf16_t* _g = (PTR); \
;     __builtin_amdgcn_global_load_lds((const unsigned*)(_g + O0), (lds_u32*)((P) + swave * 1024), 16, 0, 0); \
;     __builtin_amdgcn_global_load_lds((const unsigned*)(_g + (size_t)64 * (LD) + O0), (lds_u32*)((P) + swave * 1024 + 8192), 16, 0, 0); } while (0)
; #define LDA(dst, b, h) for (int m = 0; m < 4; ++m) for (int k = 0; k < 2; ++k) \
;     dst[m][k] = *reinterpret_cast<const bf16x8*>(SA(b, h) + lds_byte(wr * 64 + m * 16 + fr, k * 32 + fq * 8))
; #define MMA(ai, bj, At_, Bt_) do { __builtin_amdgcn_s_setprio(1); \
;     for (int m = 0; m < 4; ++m) for (int n = 0; n < 2; ++n) for (int k = 0; k < 2; ++k) \
;       acc[ai][bj][m][n] = __builtin_amdgcn_mfma_f32_16x16x32_bf16(Bt_[n][k], At_[m][k], acc[ai][bj][m][n], 0, 0, 0); \
;     __builtin_amdgcn_s_setprio(0); } while (0)
; #define WAIT_V(n) asm volatile("s_waitcnt vmcnt(" #n ")" ::: "memory")
; #define WAIT_L(n) asm volatile("s_waitcnt lgkmcnt(" #n ")" ::: "memory")
; #define BAR __builtin_amdgcn_s_barrier()
; #define SCHED __builtin_amdgcn_sched_barrier(0)
; __device__ __forceinline__ void gemm_stream(int swave, const GemmJob& J, char* shm, int vb, int G) {
;     ...
;     for (int t = 0; t < nt; t += 2) {
;     ...
;       BAR; WAIT_L(0); MMA(0, 1, At, B1); BAR;
;       LDA(At, 1, 1); STGA(SA(1, 0), xA, xA1, k2 + 1, 0);
;       BAR; WAIT_L(0); MMA(1, 0, At, B0); BAR; SCHED;
;       STG(SB(1, 1), b3 + hB, ldb, offB0);
;       WAIT_V(6); BAR; MMA(1, 1, At, B1); BAR;
;     }
	s_waitcnt lgkmcnt(0)
	s_waitcnt lgkmcnt(0)
	v_mfma_f32_16x16x32_bf16 v[112:115], v[212:215], v[180:183], v[112:115]
	v_mfma_f32_16x16x32_bf16 v[108:111], v[220:223], v[180:183], v[108:111]
	v_mfma_f32_16x16x32_bf16 v[96:99], v[212:215], v[188:191], v[96:99]
	v_mfma_f32_16x16x32_bf16 v[92:95], v[220:223], v[188:191], v[92:95]
	v_mfma_f32_16x16x32_bf16 v[80:83], v[212:215], v[196:199], v[80:83]
	v_mfma_f32_16x16x32_bf16 v[76:79], v[220:223], v[196:199], v[76:79]
	v_mfma_f32_16x16x32_bf16 v[72:75], v[212:215], v[204:207], v[72:75]
	v_mfma_f32_16x16x32_bf16 v[68:71], v[220:223], v[204:207], v[68:71]
	v_mfma_f32_16x16x32_bf16 v[112:115], v[216:219], v[184:187], v[112:115]
	v_mfma_f32_16x16x32_bf16 v[108:111], v[224:227], v[184:187], v[108:111]
	v_mfma_f32_16x16x32_bf16 v[96:99], v[216:219], v[192:195], v[96:99]
	v_mfma_f32_16x16x32_bf16 v[92:95], v[224:227], v[192:195], v[92:95]
	v_mfma_f32_16x16x32_bf16 v[80:83], v[216:219], v[200:203], v[80:83]
	v_mfma_f32_16x16x32_bf16 v[76:79], v[224:227], v[200:203], v[76:79]
	v_mfma_f32_16x16x32_bf16 v[72:75], v[216:219], v[208:211], v[72:75]
	v_mfma_f32_16x16x32_bf16 v[68:71], v[224:227], v[208:211], v[68:71]
	s_or_b32 s68, s68, 1
	s_cmp_lt_u32 s68, s36
	s_cselect_b64 vcc, -1, 0
	s_and_b64 s[2:3], vcc, exec
	s_cselect_b32 s69, s38, s37
	s_sub_i32 s2, s68, s36
	s_min_u32 s94, s68, s2
	s_and_b64 s[2:3], vcc, exec
	s_cselect_b32 s64, s64, s66
	s_cselect_b32 s52, s52, s65
	s_lshl_b64 s[2:3], s[94:95], 7
	v_cndmask_b32_e32 v2, v138, v0, vcc
	s_add_u32 s2, s52, s2
	s_addc_u32 s3, s64, s3
	v_lshlrev_b64 v[228:229], 1, v[2:3]
	s_lshl_b32 s52, s69, 7
	v_lshl_add_u64 v[230:231], s[2:3], 0, v[228:229]
	s_add_u32 s2, s2, s52
	s_mov_b32 m0, s54
	s_addc_u32 s3, s3, 0
	s_barrier
	ds_read_b128 v[180:183], v144 offset:49152
	ds_read_b128 v[184:187], v144 offset:50176
	ds_read_b128 v[188:191], v145 offset:49152
	ds_read_b128 v[192:195], v145 offset:50176
	ds_read_b128 v[196:199], v159 offset:49152
	ds_read_b128 v[200:203], v159 offset:50176
	ds_read_b128 v[204:207], v160 offset:49152
	ds_read_b128 v[208:211], v160 offset:50176
	global_load_lds_dwordx4 v[230:231], off
	v_lshl_add_u64 v[228:229], s[2:3], 0, v[228:229]
	s_mov_b32 m0, s55
	s_nop 0
	global_load_lds_dwordx4 v[228:229], off
	s_barrier
	s_waitcnt lgkmcnt(0)
	s_waitcnt lgkmcnt(0)
	v_mfma_f32_16x16x32_bf16 v[64:67], v[164:167], v[180:183], v[64:67]
	v_mfma_f32_16x16x32_bf16 v[60:63], v[172:175], v[180:183], v[60:63]
	v_mfma_f32_16x16x32_bf16 v[56:59], v[164:167], v[188:191], v[56:59]
	v_mfma_f32_16x16x32_bf16 v[52:55], v[172:175], v[188:191], v[52:55]
	v_mfma_f32_16x16x32_bf16 v[40:43], v[164:167], v[196:199], v[40:43]
	v_mfma_f32_16x16x32_bf16 v[36:39], v[172:175], v[196:199], v[36:39]
	v_mfma_f32_16x16x32_bf16 v[24:27], v[164:167], v[204:207], v[24:27]
	v_mfma_f32_16x16x32_bf16 v[20:23], v[172:175], v[204:207], v[20:23]
	v_mfma_f32_16x16x32_bf16 v[64:67], v[168:171], v[184:187], v[64:67]
	v_mfma_f32_16x16x32_bf16 v[60:63], v[176:179], v[184:187], v[60:63]
	v_mfma_f32_16x16x32_bf16 v[56:59], v[168:171], v[192:195], v[56:59]
	v_mfma_f32_16x16x32_bf16 v[52:55], v[176:179], v[192:195], v[52:55]
	v_mfma_f32_16x16x32_bf16 v[40:43], v[168:171], v[200:203], v[40:43]
	v_mfma_f32_16x16x32_bf16 v[36:39], v[176:179], v[200:203], v[36:39]
	v_mfma_f32_16x16x32_bf16 v[24:27], v[168:171], v[208:211], v[24:27]
	v_mfma_f32_16x16x32_bf16 v[20:23], v[176:179], v[208:211], v[20:23]
	s_barrier
	v_lshl_add_u64 v[164:165], v[234:235], 0, s[22:23]
	s_add_i32 m0, s42, 0x1c000
	s_nop 0
	global_load_lds_dwordx4 v[164:165], off
	v_lshl_add_u64 v[164:165], v[236:237], 0, s[22:23]
	s_add_i32 m0, s42, 0x1e000
	s_nop 0
	global_load_lds_dwordx4 v[164:165], off
	s_waitcnt vmcnt(6)
	s_barrier
	v_mfma_f32_16x16x32_bf16 v[48:51], v[212:215], v[180:183], v[48:51]
	v_mfma_f32_16x16x32_bf16 v[44:47], v[220:223], v[180:183], v[44:47]
	v_mfma_f32_16x16x32_bf16 v[32:35], v[212:215], v[188:191], v[32:35]
	v_mfma_f32_16x16x32_bf16 v[28:31], v[220:223], v[188:191], v[28:31]
	v_mfma_f32_16x16x32_bf16 v[16:19], v[212:215], v[196:199], v[16:19]
	v_mfma_f32_16x16x32_bf16 v[12:15], v[220:223], v[196:199], v[12:15]
	v_mfma_f32_16x16x32_bf16 v[8:11], v[212:215], v[204:207], v[8:11]
	v_mfma_f32_16x16x32_bf16 v[4:7], v[220:223], v[204:207], v[4:7]
	v_mfma_f32_16x16x32_bf16 v[48:51], v[216:219], v[184:187], v[48:51]
	v_mfma_f32_16x16x32_bf16 v[44:47], v[224:227], v[184:187], v[44:47]
	v_mfma_f32_16x16x32_bf16 v[32:35], v[216:219], v[192:195], v[32:35]
	v_mfma_f32_16x16x32_bf16 v[28:31], v[224:227], v[192:195], v[28:31]
	v_mfma_f32_16x16x32_bf16 v[16:19], v[216:219], v[200:203], v[16:19]
	v_mfma_f32_16x16x32_bf16 v[12:15], v[224:227], v[200:203], v[12:15]
	v_mfma_f32_16x16x32_bf16 v[8:11], v[216:219], v[208:211], v[8:11]
	v_mfma_f32_16x16x32_bf16 v[4:7], v[224:227], v[208:211], v[4:7]
	s_add_i32 s29, s29, 2
	s_add_u32 s20, s20, 0x100
	s_addc_u32 s21, s21, 0
	s_cmp_ge_u32 s33, s49
	s_mov_b32 s2, s33
	s_barrier
	s_cbranch_scc0 .LBB0_729
; __device__ __forceinline__ unsigned pk2(float lo, float hi) { f32x2_t v = {lo, hi}; bf16x2_t b = __builtin_convertvector(v, bf16x2_t); return __builtin_bit_cast(unsigned, b); }
; #define WAIT_V(n) asm volatile("s_waitcnt vmcnt(" #n ")" ::: "memory")
; #define BAR __builtin_amdgcn_s_barrier()
; #define WAIT_V(n) asm volatile("s_waitcnt vmcnt(" #n ")" ::: "memory")
; #define BAR __builtin_amdgcn_s_barrier()
; __device__ __forceinline__ void gemm_stream(int swave, const GemmJob& J, char* shm, int vb, int G) {
;     ...
;     {
;       bf16_t* C = (bf16_t*)((char*)J.c0 + (size_t)cg * J.strideC);
; #pragma unroll
;       for (int ai = 0; ai < 2; ++ai)
; #pragma unroll
;         for (int m = 0; m < 4; ++m)
; #pragma unroll
;           for (int bj = 0; bj < 2; ++bj) {
;             const f32x4 v0 = acc[ai][bj][m][0], v1 = acc[ai][bj][m][1];
;             uint4 o; o.x = pk2(v0[0], v0[1]); o.y = pk2(v0[2], v0[3]); o.z = pk2(v1[0], v1[1]); o.w = pk2(v1[2], v1[3]);
;             *(uint4*)(C + (size_t)(cbrow + ai * 128 + wr * 64 + m * 16 + fr) * J.ldc + cbcol + bj * 128 + wc * 32 + fq * 8) = o;
;           }
;     }
;     if (!has_next) break;
; #pragma unroll
;     for (int a_ = 0; a_ < 2; ++a_)
; #pragma unroll
;       for (int b_ = 0; b_ < 2; ++b_)
; #pragma unroll
;         for (int m = 0; m < 4; ++m)
; #pragma unroll
;           for (int n = 0; n < 2; ++n) acc[a_][b_][m][n] = (f32x4){0.f, 0.f, 0.f, 0.f};
;     id = nid; cg = ng; cbrow = nbrow; cbcol = nbcol; cA = nA; cA1 = nA1; cB = nB;
;   }
;   WAIT_V(0);
;   if (wr == 0) BAR;
;   BAR;
	v_add_u32_e32 v164, s5, v1
	s_ashr_i32 s5, s4, 31
	s_lshl_b64 s[2:3], s[4:5], 1
	v_ashrrev_i32_e32 v2, 31, v164
	s_add_u32 s2, s50, s2
	v_cvt_pk_bf16_f32 v128, v128, v129
	v_cvt_pk_bf16_f32 v129, v130, v131
	v_cvt_pk_bf16_f32 v130, v124, v125
	v_mul_lo_u32 v2, v2, s18
	v_mad_u64_u32 v[124:125], s[4:5], v164, s18, 0
	s_addc_u32 s3, s51, s3
	v_add_u32_e32 v125, v125, v2
	v_lshl_add_u64 v[124:125], v[124:125], 1, s[2:3]
	v_mov_b32_e32 v141, v3
	v_lshl_add_u64 v[124:125], v[124:125], 0, v[140:141]
	v_mov_b32_e32 v143, v3
	v_lshl_add_u64 v[124:125], v[124:125], 0, v[142:143]
	v_cvt_pk_bf16_f32 v112, v112, v113
	v_cvt_pk_bf16_f32 v113, v114, v115
	v_cvt_pk_bf16_f32 v114, v108, v109
	v_cvt_pk_bf16_f32 v115, v110, v111
	global_store_dwordx4 v[124:125], v[112:115], off offset:256
	v_cvt_pk_bf16_f32 v131, v126, v127
	v_cvt_pk_bf16_f32 v96, v96, v97
	v_or_b32_e32 v112, 16, v164
	v_mad_u64_u32 v[112:113], s[4:5], v112, s18, 0
	v_add_u32_e32 v113, v113, v2
	v_lshl_add_u64 v[112:113], v[112:113], 1, s[2:3]
	v_lshl_add_u64 v[112:113], v[112:113], 0, v[140:141]
	v_lshl_add_u64 v[112:113], v[112:113], 0, v[142:143]
	v_cvt_pk_bf16_f32 v97, v98, v99
	v_cvt_pk_bf16_f32 v98, v92, v93
	v_cvt_pk_bf16_f32 v99, v94, v95
	global_store_dwordx4 v[124:125], v[128:131], off
	global_store_dwordx4 v[112:113], v[96:99], off offset:256
	v_cvt_pk_bf16_f32 v108, v120, v121
	v_cvt_pk_bf16_f32 v109, v122, v123
	v_or_b32_e32 v96, 32, v164
	v_mad_u64_u32 v[96:97], s[4:5], v96, s18, 0
	v_add_u32_e32 v97, v97, v2
	v_lshl_add_u64 v[96:97], v[96:97], 1, s[2:3]
	v_lshl_add_u64 v[96:97], v[96:97], 0, v[140:141]
	v_cvt_pk_bf16_f32 v110, v116, v117
	v_cvt_pk_bf16_f32 v111, v118, v119
	v_lshl_add_u64 v[96:97], v[96:97], 0, v[142:143]
	v_cvt_pk_bf16_f32 v80, v80, v81
	v_cvt_pk_bf16_f32 v81, v82, v83
	v_cvt_pk_bf16_f32 v82, v76, v77
	v_cvt_pk_bf16_f32 v83, v78, v79
	global_store_dwordx4 v[112:113], v[108:111], off
	global_store_dwordx4 v[96:97], v[80:83], off offset:256
	v_cvt_pk_bf16_f32 v64, v64, v65
	v_cvt_pk_bf16_f32 v65, v66, v67
	v_or_b32_e32 v80, 48, v164
	v_mad_u64_u32 v[80:81], s[4:5], v80, s18, 0
	v_add_u32_e32 v81, v81, v2
	v_add_u32_e32 v2, 0x80, v164
	v_cvt_pk_bf16_f32 v66, v60, v61
	v_mad_u64_u32 v[60:61], s[4:5], v2, s18, 0
	v_cvt_pk_bf16_f32 v72, v72, v73
	v_cvt_pk_bf16_f32 v73, v74, v75
	v_cvt_pk_bf16_f32 v74, v68, v69
	v_ashrrev_i32_e32 v68, 31, v2
	v_mov_b32_e32 v2, v61
	v_cvt_pk_bf16_f32 v67, v62, v63
	v_mad_u64_u32 v[62:63], s[4:5], v68, s18, v[2:3]
	v_mov_b32_e32 v61, v62
	v_lshl_add_u64 v[80:81], v[80:81], 1, s[2:3]
	v_lshl_add_u64 v[60:61], v[60:61], 1, s[2:3]
	v_lshl_add_u64 v[80:81], v[80:81], 0, v[140:141]
	v_lshl_add_u64 v[60:61], v[60:61], 0, v[140:141]
	v_cvt_pk_bf16_f32 v92, v104, v105
	v_cvt_pk_bf16_f32 v93, v106, v107
	v_cvt_pk_bf16_f32 v94, v100, v101
	v_cvt_pk_bf16_f32 v95, v102, v103
	v_cvt_pk_bf16_f32 v76, v88, v89
	v_cvt_pk_bf16_f32 v77, v90, v91
	v_cvt_pk_bf16_f32 v78, v84, v85
	v_cvt_pk_bf16_f32 v79, v86, v87
	v_lshl_add_u64 v[80:81], v[80:81], 0, v[142:143]
	v_cvt_pk_bf16_f32 v75, v70, v71
	v_lshl_add_u64 v[60:61], v[60:61], 0, v[142:143]
	v_cvt_pk_bf16_f32 v48, v48, v49
	v_cvt_pk_bf16_f32 v49, v50, v51
	v_cvt_pk_bf16_f32 v50, v44, v45
	v_cvt_pk_bf16_f32 v51, v46, v47
	v_add_u32_e32 v2, 0x90, v164
	global_store_dwordx4 v[96:97], v[92:95], off
	global_store_dwordx4 v[80:81], v[76:79], off
	global_store_dwordx4 v[80:81], v[72:75], off offset:256
	global_store_dwordx4 v[60:61], v[48:51], off offset:256
	v_cvt_pk_bf16_f32 v32, v32, v33
	v_cvt_pk_bf16_f32 v33, v34, v35
	v_mad_u64_u32 v[48:49], s[4:5], v2, s18, 0
	v_ashrrev_i32_e32 v50, 31, v2
	v_mov_b32_e32 v2, v49
	v_mad_u64_u32 v[50:51], s[4:5], v50, s18, v[2:3]
	v_mov_b32_e32 v49, v50
	v_lshl_add_u64 v[48:49], v[48:49], 1, s[2:3]
	v_lshl_add_u64 v[48:49], v[48:49], 0, v[140:141]
	v_lshl_add_u64 v[48:49], v[48:49], 0, v[142:143]
	v_cvt_pk_bf16_f32 v34, v28, v29
	v_cvt_pk_bf16_f32 v35, v30, v31
	v_add_u32_e32 v2, 0xa0, v164
	global_store_dwordx4 v[60:61], v[64:67], off
	global_store_dwordx4 v[48:49], v[32:35], off offset:256
	v_cvt_pk_bf16_f32 v44, v56, v57
	v_cvt_pk_bf16_f32 v45, v58, v59
	v_mad_u64_u32 v[32:33], s[4:5], v2, s18, 0
	v_ashrrev_i32_e32 v34, 31, v2
	v_mov_b32_e32 v2, v33
	v_mad_u64_u32 v[34:35], s[4:5], v34, s18, v[2:3]
	v_mov_b32_e32 v33, v34
	v_lshl_add_u64 v[32:33], v[32:33], 1, s[2:3]
	v_lshl_add_u64 v[32:33], v[32:33], 0, v[140:141]
	v_cvt_pk_bf16_f32 v46, v52, v53
	v_cvt_pk_bf16_f32 v47, v54, v55
	v_lshl_add_u64 v[32:33], v[32:33], 0, v[142:143]
	v_cvt_pk_bf16_f32 v16, v16, v17
	v_cvt_pk_bf16_f32 v17, v18, v19
	v_cvt_pk_bf16_f32 v18, v12, v13
	v_cvt_pk_bf16_f32 v19, v14, v15
	v_add_u32_e32 v2, 0xb0, v164
	global_store_dwordx4 v[48:49], v[44:47], off
	global_store_dwordx4 v[32:33], v[16:19], off offset:256
	v_cvt_pk_bf16_f32 v28, v40, v41
	v_cvt_pk_bf16_f32 v29, v42, v43
	v_mad_u64_u32 v[16:17], s[4:5], v2, s18, 0
	v_ashrrev_i32_e32 v18, 31, v2
	v_mov_b32_e32 v2, v17
	v_mad_u64_u32 v[18:19], s[4:5], v18, s18, v[2:3]
	v_mov_b32_e32 v17, v18
	v_lshl_add_u64 v[16:17], v[16:17], 1, s[2:3]
	v_lshl_add_u64 v[16:17], v[16:17], 0, v[140:141]
	v_cvt_pk_bf16_f32 v30, v36, v37
	v_cvt_pk_bf16_f32 v31, v38, v39
	v_cvt_pk_bf16_f32 v12, v24, v25
	v_cvt_pk_bf16_f32 v13, v26, v27
	v_cvt_pk_bf16_f32 v14, v20, v21
	v_cvt_pk_bf16_f32 v15, v22, v23
	v_lshl_add_u64 v[16:17], v[16:17], 0, v[142:143]
	v_cvt_pk_bf16_f32 v8, v8, v9
	v_cvt_pk_bf16_f32 v9, v10, v11
	v_cvt_pk_bf16_f32 v10, v4, v5
	v_cvt_pk_bf16_f32 v11, v6, v7
	s_and_b64 vcc, exec, s[6:7]
	s_mov_b64 s[2:3], s[14:15]
	s_mov_b64 s[16:17], s[12:13]
	s_mov_b64 s[8:9], s[10:11]
	s_mov_b32 s4, s56
	s_mov_b32 s5, s28
	global_store_dwordx4 v[32:33], v[28:31], off
	global_store_dwordx4 v[16:17], v[12:15], off
	global_store_dwordx4 v[16:17], v[8:11], off offset:256
	s_cbranch_vccz .LBB0_726
	s_waitcnt vmcnt(0)
	s_movk_i32 s66, 0x100
	v_cmp_gt_u32_e32 vcc, s66, v135
	s_and_saveexec_b64 s[0:1], vcc
	s_cbranch_execz .LBB0_733
	s_barrier
